# out-proj tail tiles: 16 split-K parts of 2 K-tiles on 128 workgroups instead of 4 parts of 8 on 32; fix-up sums 16 partials for the 64 real rows (on v84)
# speedup vs baseline: 1.0053x; 1.0053x over previous
.LBB0_59:
	s_or_b64 exec, exec, s[4:5]
	s_add_u32 s4, s76, 0x800
	s_addc_u32 s5, s77, 0
	v_writelane_b32 v252, s4, 39
	s_add_u32 s3, s76, 0x10120000
	v_lshrrev_b32_e32 v165, 4, v164
	v_writelane_b32 v252, s5, 40
	v_writelane_b32 v252, s3, 41
	s_addc_u32 s3, s77, 0
	v_writelane_b32 v252, s3, 42
	s_add_u32 s3, s76, 0x10340000
	v_writelane_b32 v252, s3, 43
	s_addc_u32 s3, s77, 0
	s_add_u32 s4, s76, 0x1300000
	v_writelane_b32 v252, s3, 44
	s_addc_u32 s5, s77, 0
	v_writelane_b32 v252, s4, 45
	v_mbcnt_lo_u32_b32 v209, -1, 0
	v_lshl_add_u32 v204, v164, 4, 0
	v_writelane_b32 v252, s5, 46
	s_add_u32 s4, s76, 0x1b00000
	s_addc_u32 s5, s77, 0
	v_writelane_b32 v252, s4, 47
	v_mov_b32_e32 v205, 0x358637bd
	v_mov_b32_e32 v211, 1
	v_writelane_b32 v252, s5, 48
	s_add_u32 s4, s76, 0x3b00000
	s_addc_u32 s5, s77, 0
	v_writelane_b32 v252, s4, 49
	v_mov_b32_e32 v208, 0x3c23d70a
	v_mbcnt_hi_u32_b32 v210, -1, v209
	v_writelane_b32 v252, s5, 50
	s_add_u32 s4, s76, 0x5b00000
	s_addc_u32 s5, s77, 0
	v_writelane_b32 v252, s4, 51
	v_mov_b32_e32 v112, 0
	v_mov_b32_e32 v212, 0xf149f2ca
	v_writelane_b32 v252, s5, 52
	s_add_u32 s4, s76, 0x7300000
	s_addc_u32 s5, s77, 0
	v_writelane_b32 v252, s4, 53
	v_mov_b64_e32 v[174:175], 0xff
	v_mov_b64_e32 v[176:177], 0x440
	v_writelane_b32 v252, s5, 54
	s_add_u32 s4, s76, 0x7b00000
	s_addc_u32 s5, s77, 0
	v_writelane_b32 v252, s4, 55
	v_mov_b64_e32 v[178:179], 0x43f
	v_mov_b64_e32 v[180:181], 0x200
	v_writelane_b32 v252, s5, 56
	s_add_u32 s4, s76, 0x9b00000
	s_addc_u32 s5, s77, 0
	s_add_u32 s10, s76, 0x12100000
	s_addc_u32 s11, s77, 0
	s_add_u32 s86, s76, 0x16500000
	v_writelane_b32 v252, s4, 57
	s_addc_u32 s87, s77, 0
	v_mov_b64_e32 v[182:183], 0x1ff
	v_writelane_b32 v252, s5, 58
	s_add_u32 s4, s76, 0x18700000
	s_addc_u32 s5, s77, 0
	v_writelane_b32 v252, s4, 59
	s_add_u32 s26, s76, 0x1a900000
	s_addc_u32 s27, s77, 0
	v_writelane_b32 v252, s5, 60
	s_ashr_i32 s31, s82, 31
	v_readlane_b32 s36, v252, 23
	s_ashr_i32 s3, s2, 31
	v_readlane_b32 s44, v252, 31
	v_readlane_b32 s45, v252, 32
	s_add_u32 s4, s44, 0x4000000
	s_addc_u32 s5, s45, 0
	v_readlane_b32 s37, v252, 24
	v_readlane_b32 s38, v252, 25
	v_readlane_b32 s39, v252, 26
	v_readlane_b32 s40, v252, 27
	v_readlane_b32 s41, v252, 28
	v_readlane_b32 s42, v252, 29
	v_readlane_b32 s43, v252, 30
	v_readlane_b32 s46, v252, 33
	v_readlane_b32 s47, v252, 34
	v_readlane_b32 s48, v252, 35
	v_readlane_b32 s49, v252, 36
	v_readlane_b32 s50, v252, 37
	v_readlane_b32 s51, v252, 38
	v_writelane_b32 v252, s4, 61
	s_add_u32 s18, s42, 0x2000
	s_addc_u32 s19, s43, 0
	v_writelane_b32 v252, s5, 62
	s_movk_i32 s91, 0x6000
	v_readlane_b32 s34, v252, 22
	s_lshl_b32 s74, s34, 2
	s_cmp_lg_u64 s[42:43], 0
	s_cselect_b64 s[20:21], -1, 0
	s_add_u32 s84, s76, 0x40200
	s_addc_u32 s85, s77, 0
	s_add_u32 s58, s76, 0x40400
	s_addc_u32 s59, s77, 0
	s_add_u32 s60, s76, 0x40500
	s_addc_u32 s61, s77, 0
	s_add_u32 s62, s76, 0x40600
	s_addc_u32 s63, s77, 0
	s_add_u32 s56, s76, 0x40700
	s_addc_u32 s57, s77, 0
	s_add_u32 s22, s76, 0x40800
	s_addc_u32 s23, s77, 0
	s_add_u32 s4, s76, 0x40900
	s_addc_u32 s5, s77, 0
	v_writelane_b32 v252, s4, 63
	v_writelane_b32 v255, s84, 0
	s_movk_i32 s94, 0x1fff
	v_writelane_b32 v253, s5, 0
	s_add_u32 s4, s76, 0x40a00
	s_addc_u32 s5, s77, 0
	v_writelane_b32 v253, s4, 1
	v_writelane_b32 v255, s85, 1
	v_writelane_b32 v255, s58, 2
	v_writelane_b32 v253, s5, 2
	s_add_u32 s4, s76, 0x40b00
	s_addc_u32 s5, s77, 0
	v_writelane_b32 v253, s4, 3
	v_writelane_b32 v255, s59, 3
	v_writelane_b32 v255, s60, 4
	v_writelane_b32 v253, s5, 4
	s_add_u32 s4, s76, 0x40c00
	s_addc_u32 s5, s77, 0
	v_writelane_b32 v253, s4, 5
	v_writelane_b32 v255, s61, 5
	v_writelane_b32 v255, s62, 6
	v_writelane_b32 v253, s5, 6
	s_add_u32 s4, s76, 0x40d00
	s_addc_u32 s5, s77, 0
	v_writelane_b32 v253, s4, 7
	v_writelane_b32 v255, s63, 7
	v_writelane_b32 v255, s56, 8
	v_writelane_b32 v253, s5, 8
	s_add_u32 s4, s76, 0x40e00
	s_addc_u32 s5, s77, 0
	v_writelane_b32 v253, s4, 9
	v_writelane_b32 v255, s57, 9
	s_nop 0
	v_writelane_b32 v253, s5, 10
	s_add_u32 s4, s76, 0x40f00
	s_addc_u32 s5, s77, 0
	v_writelane_b32 v253, s4, 11
	s_nop 1
	v_writelane_b32 v253, s5, 12
	s_add_u32 s4, s76, 0x41000
	s_addc_u32 s5, s77, 0
	v_writelane_b32 v253, s4, 13
	s_nop 1
	v_writelane_b32 v253, s5, 14
	s_add_u32 s4, s76, 0x41100
	s_addc_u32 s5, s77, 0
	v_writelane_b32 v253, s4, 15
	s_nop 1
	v_writelane_b32 v253, s5, 16
	s_add_u32 s4, s76, 0x41200
	s_addc_u32 s5, s77, 0
	v_writelane_b32 v253, s4, 17
	s_nop 1
	v_writelane_b32 v253, s5, 18
	s_add_u32 s4, s76, 0x41300
	s_addc_u32 s5, s77, 0
	v_writelane_b32 v253, s4, 19
	s_cmp_eq_u32 s8, 15
	s_nop 0
	v_writelane_b32 v253, s5, 20
	s_cselect_b64 s[4:5], -1, 0
	v_writelane_b32 v253, s4, 21
	s_cmp_eq_u32 s8, 14
	s_nop 0
	v_writelane_b32 v253, s5, 22
	s_cselect_b64 s[4:5], -1, 0
	v_writelane_b32 v253, s4, 23
	s_cmp_eq_u32 s8, 13
	s_nop 0
	v_writelane_b32 v253, s5, 24
	s_cselect_b64 s[4:5], -1, 0
	v_writelane_b32 v253, s4, 25
	s_cmp_eq_u32 s8, 12
	s_nop 0
	v_writelane_b32 v253, s5, 26
	s_cselect_b64 s[4:5], -1, 0
	v_writelane_b32 v253, s4, 27
	s_cmp_eq_u32 s8, 11
	s_nop 0
	v_writelane_b32 v253, s5, 28
	s_cselect_b64 s[4:5], -1, 0
	v_writelane_b32 v253, s4, 29
	s_cmp_eq_u32 s8, 10
	s_nop 0
	v_writelane_b32 v253, s5, 30
	s_cselect_b64 s[4:5], -1, 0
	v_writelane_b32 v253, s4, 31
	s_cmp_eq_u32 s8, 9
	s_nop 0
	v_writelane_b32 v253, s5, 32
	s_cselect_b64 s[4:5], -1, 0
	v_writelane_b32 v253, s4, 33
	s_cmp_eq_u32 s8, 8
	s_nop 0
	v_writelane_b32 v253, s5, 34
	s_cselect_b64 s[4:5], -1, 0
	v_writelane_b32 v253, s4, 35
	s_cmp_eq_u32 s8, 7
	s_nop 0
	v_writelane_b32 v253, s5, 36
	s_cselect_b64 s[4:5], -1, 0
	v_writelane_b32 v253, s4, 37
	s_cmp_eq_u32 s8, 6
	s_nop 0
	v_writelane_b32 v253, s5, 38
	s_cselect_b64 s[4:5], -1, 0
	v_writelane_b32 v253, s4, 39
	s_cmp_eq_u32 s8, 5
	s_nop 0
	v_writelane_b32 v253, s5, 40
	s_cselect_b64 s[4:5], -1, 0
	v_writelane_b32 v253, s4, 41
	s_cmp_eq_u32 s8, 4
	s_nop 0
	v_writelane_b32 v253, s5, 42
	s_cselect_b64 s[4:5], -1, 0
	v_writelane_b32 v253, s4, 43
	s_cmp_eq_u32 s8, 3
	s_nop 0
	v_writelane_b32 v253, s5, 44
	s_cselect_b64 s[4:5], -1, 0
	v_writelane_b32 v253, s4, 45
	s_cmp_eq_u32 s8, 2
	s_nop 0
	v_writelane_b32 v253, s5, 46
	s_cselect_b64 s[4:5], -1, 0
	v_writelane_b32 v253, s4, 47
	s_cmp_eq_u32 s8, 1
	s_nop 0
	v_writelane_b32 v253, s5, 48
	s_cselect_b64 s[4:5], -1, 0
	v_writelane_b32 v253, s4, 49
	s_cmp_eq_u32 s8, 0
	s_nop 0
	v_writelane_b32 v253, s5, 50
	s_cselect_b64 s[4:5], -1, 0
	v_writelane_b32 v253, s4, 51
	s_nop 1
	v_writelane_b32 v253, s5, 52
	s_lshl_b32 s4, s9, 2
	s_add_u32 s4, s16, s4
	s_addc_u32 s5, s17, 0
	s_add_u32 s6, s4, 0x1400
	s_addc_u32 s7, s5, 0
	v_writelane_b32 v253, s6, 53
	s_add_u32 s4, s4, 0x2400
	s_addc_u32 s5, s5, 0
	v_writelane_b32 v253, s7, 54
	v_writelane_b32 v253, s4, 55
	s_nop 1
	v_writelane_b32 v253, s5, 56
	s_add_u32 s4, s76, 0x43400
	s_addc_u32 s5, s77, 0
	v_writelane_b32 v253, s4, 57
	s_nop 1
	v_writelane_b32 v253, s5, 58
	s_add_u32 s4, s76, 0x43500
	s_addc_u32 s5, s77, 0
	v_writelane_b32 v253, s4, 59
	s_lshr_b32 s6, s25, 7
	s_bfe_u32 s7, s25, 0x10006
	v_writelane_b32 v253, s5, 60
	s_lshl_b32 s4, s34, 4
	s_and_b32 s28, s4, 0x3fffffe0
	s_lshl_b32 s4, s6, 14
	s_add_i32 s4, s4, 0
	v_writelane_b32 v253, s4, 61
	s_lshl_b32 s4, s2, 9
	v_writelane_b32 v253, s4, 62
	s_lshl_b32 s5, s7, 1
	s_lshl_b32 s4, s7, 6
	s_lshl_b32 s90, s7, 14
	s_add_i32 s29, 0, 0x20080
	s_and_b32 s8, 64, s25
	s_lshl_b32 s36, s82, 9
	s_cmp_eq_u32 s7, 0
	s_cselect_b64 s[12:13], -1, 0
	s_cmp_lg_u32 s8, 0
	v_writelane_b32 v253, s12, 63
	s_cselect_b64 s[8:9], -1, 0
	s_lshl_b32 s6, s6, 5
	v_writelane_b32 v254, s13, 0
	v_writelane_b32 v254, s8, 1
	s_cmpk_lt_i32 s2, 0x120
	v_lshl_add_u32 v203, v164, 2, s29
	v_writelane_b32 v254, s9, 2
	v_writelane_b32 v254, s6, 3
	s_cselect_b64 s[6:7], -1, 0
	v_writelane_b32 v254, s6, 4
	s_lshl_b32 s14, s2, 3
	s_add_i32 s16, s34, s14
	v_writelane_b32 v254, s7, 5
	s_lshr_b32 s6, s3, 29
	s_add_i32 s6, s2, s6
	s_ashr_i32 s30, s6, 3
	s_lshl_b32 s7, s2, 5
	s_mul_i32 s8, s30, 0xffffff01
	s_add_i32 s7, s8, s7
	s_ashr_i32 s8, s7, 31
	s_lshr_b32 s8, s8, 26
	s_add_i32 s8, s7, s8
	s_and_b32 s9, s8, 0xffffffc0
	s_sub_i32 s7, s7, s9
	s_bfe_i32 s9, s7, 0x80000
	s_bfe_u32 s9, s9, 0x3000c
	s_add_i32 s9, s7, s9
	s_and_b32 s12, s9, 0xf8
	s_sub_i32 s7, s7, s12
	s_ashr_i32 s8, s8, 6
	s_lshl_b32 s8, s8, 3
	s_sext_i32_i8 s7, s7
	s_add_i32 s8, s8, s7
	s_bfe_i32 s7, s9, 0x80000
	s_sext_i32_i16 s7, s7
	s_and_b32 s9, s2, 3
	s_lshl_b32 s14, s16, 6
	s_ashr_i32 s7, s7, 3
	s_bfe_u32 s12, s2, 0x30002
	s_lshl_b32 s13, s9, 10
	s_lshl_b32 s73, s82, 3
	v_writelane_b32 v254, s14, 6
	s_mov_b32 s14, s16
	v_writelane_b32 v254, s14, 7
	s_cmpk_lt_i32 s16, 0x800
	s_nop 0
	v_writelane_b32 v254, s15, 8
	s_cselect_b64 s[14:15], -1, 0
	v_writelane_b32 v254, s14, 9
	s_cmpk_lt_i32 s2, 0x420
	s_nop 0
	v_writelane_b32 v254, s15, 10
	s_cselect_b64 s[14:15], -1, 0
	s_and_b32 s6, s6, -8
	v_writelane_b32 v254, s14, 11
	s_sub_i32 s33, s2, s6
	s_nop 0
	v_writelane_b32 v254, s15, 12
	s_add_u32 s14, s46, 0x4000000
	s_addc_u32 s15, s47, 0
	v_readlane_b32 s40, v252, 0
	v_readlane_b32 s52, v252, 12
	v_readlane_b32 s53, v252, 13
	v_readlane_b32 s50, v252, 10
	v_readlane_b32 s51, v252, 11
	s_cmp_lg_u64 s[52:53], 0
	v_writelane_b32 v254, s14, 13
	s_cselect_b64 s[50:51], -1, 0
	s_cmpk_lt_i32 s2, 0x140
	v_writelane_b32 v254, s15, 14
	s_cselect_b64 s[14:15], -1, 0
	v_writelane_b32 v254, s14, 15
	s_bfe_u32 s6, s25, 0x30006
	s_lshl_b32 s17, s6, 8
	v_writelane_b32 v254, s15, 16
	s_and_b32 s14, s2, 7
	v_writelane_b32 v254, s17, 17
	s_lshl_b32 s17, s6, 2
	v_readlane_b32 s54, v252, 14
	v_readlane_b32 s55, v252, 15
	s_bfe_u32 s15, s2, 0x30003
	s_lshl_b32 s16, s14, 11
	v_writelane_b32 v254, s17, 18
	s_lshl_b32 s17, s6, 22
	s_mov_b64 s[54:55], s[22:23]
	s_add_u32 s22, s26, s17
	s_addc_u32 s23, s27, 0
	s_cmp_lt_i32 s33, 0
	s_movk_i32 s17, 0x85
	s_movk_i32 s17, 0x80
	s_mul_i32 s17, s33, s17
	v_writelane_b32 v254, s22, 19
	s_add_i32 s17, s17, s30
	s_add_i32 s22, s2, 0x320
	s_cmpk_ge_u32 s2, 0xe0
	s_cselect_b32 s17, s22, s17
	v_writelane_b32 v255, s54, 10
	v_writelane_b32 v254, s23, 20
	s_ashr_i32 s22, s17, 31
	s_lshr_b32 s22, s22, 24
	s_add_i32 s22, s17, s22
	s_and_b32 s23, s22, 0xffffff00
	s_ashr_i32 s22, s22, 8
	s_lshl_b32 s22, s22, 3
	s_sub_i32 s17, s17, s23
	s_sub_i32 s23, 33, s22
	s_min_i32 s23, s23, 8
	v_writelane_b32 v254, s33, 21
	s_cmpk_lt_i32 s2, 0x100
	v_writelane_b32 v254, s30, 22
	s_cselect_b32 s88, 0, s13
	v_writelane_b32 v254, s88, 23
	s_cselect_b32 s12, s7, s12
	s_cselect_b32 s7, s7, s15
	v_writelane_b32 v254, s89, 24
	v_writelane_b32 v254, s12, 25
	v_writelane_b32 v254, s7, 26
	s_cselect_b32 s7, s8, 32
	v_writelane_b32 v254, s7, 27
	s_cselect_b32 s7, -1, s9
	v_writelane_b32 v254, s7, 28
	s_cselect_b32 s7, -1, s14
	v_writelane_b32 v254, s7, 29
	s_cselect_b32 s7, 32, 8
	v_writelane_b32 v254, s7, 30
	s_cselect_b32 s7, 0x80, 16
	v_writelane_b32 v254, s7, 31
	s_sext_i32_i16 s7, s23
	v_cvt_f32_i32_e32 v0, s7
	v_cvt_f32_i32_e32 v1, s17
	s_cselect_b32 s88, 0, s16
	s_lshl_b32 s6, s6, 23
	v_rcp_iflag_f32_e32 v2, v0
	s_add_u32 s8, s26, s6
	v_writelane_b32 v254, s26, 32
	s_addc_u32 s9, s27, 0
	v_mul_f32_e32 v2, v1, v2
	v_writelane_b32 v254, s27, 33
	s_xor_b32 s6, s17, s7
	v_trunc_f32_e32 v2, v2
	v_writelane_b32 v254, s8, 34
	s_ashr_i32 s6, s6, 30
	v_fma_f32 v1, -v2, v0, v1
	v_writelane_b32 v254, s9, 35
	s_or_b32 s8, s6, 1
	v_cmp_ge_f32_e64 s[6:7], |v1|, |v0|
	v_cvt_i32_f32_e32 v0, v2
	s_and_b64 s[6:7], s[6:7], exec
	s_mul_i32 s6, s83, s82
	s_mul_i32 s6, s6, s24
	v_writelane_b32 v254, s6, 36
	s_cselect_b32 s6, s8, 0
	v_readfirstlane_b32 s7, v0
	s_add_i32 s6, s7, s6
	s_mul_i32 s7, s6, s23
	s_sub_i32 s7, s17, s7
	s_sext_i32_i16 s7, s7
	s_add_i32 s7, s22, s7
	v_writelane_b32 v254, s7, 37
	v_writelane_b32 v254, s29, 38
	s_sext_i32_i16 s6, s6
	v_writelane_b32 v254, s6, 39
	s_lshl_b32 s6, s34, 7
	v_writelane_b32 v254, s6, 40
	s_add_u32 s6, s76, 0x1a740000
	s_addc_u32 s7, s77, 0
	v_writelane_b32 v254, s6, 41
	s_lshl_b32 s5, s5, 2
	s_lshl_b32 s4, s4, 1
	v_writelane_b32 v254, s7, 42
	v_writelane_b32 v254, s5, 43
	v_writelane_b32 v254, s28, 44
	s_add_i32 s5, s28, 0x800
	v_writelane_b32 v254, s5, 45
	s_add_i32 s5, 0, 0x20040
	v_writelane_b32 v254, s5, 46
	s_add_i32 s5, 0, 0x20044
	v_writelane_b32 v254, s5, 47
	v_writelane_b32 v254, s4, 48
	v_cmp_gt_u32_e64 s[6:7], 3, v164
	s_ashr_i32 s37, s36, 31
	v_writelane_b32 v254, s5, 49
	s_add_i32 s4, 0, 0x20084
	v_writelane_b32 v254, s4, 50
	v_writelane_b32 v254, s6, 51
	s_lshl_b64 s[64:65], s[36:37], 4
	v_writelane_b32 v255, s55, 11
	v_writelane_b32 v254, s7, 52
	v_writelane_b32 v254, s88, 53
	s_lshl_b64 s[6:7], s[36:37], 7
	v_xor_b32_e32 v0, v165, v164
	v_writelane_b32 v254, s89, 54
	v_writelane_b32 v254, s6, 55
	v_writelane_b32 v255, s64, 12
	v_lshlrev_b32_e32 v1, 3, v0
	v_writelane_b32 v254, s7, 56
	s_mov_b64 s[6:7], -1
	v_writelane_b32 v254, s6, 57
	s_lshl_b64 s[92:93], s[36:37], 2
	v_writelane_b32 v255, s65, 13
	v_writelane_b32 v254, s7, 58
	v_writelane_b32 v254, s72, 59
	v_writelane_b32 v254, s73, 60
	v_writelane_b32 v254, s86, 61
	v_and_b32_e32 v2, 56, v1
	v_mov_b32_e32 v0, 0
	v_and_b32_e32 v4, 0x78, v1
	v_writelane_b32 v254, s87, 62
	v_writelane_b32 v255, s92, 14
	v_mov_b32_e32 v113, v0
	v_mov_b32_e32 v114, v0
	v_mov_b32_e32 v115, v0
	v_lshlrev_b32_e32 v166, 1, v4
	v_lshlrev_b32_e32 v168, 1, v2
	s_mov_b32 s83, 0xffff0000
	s_mov_b32 s12, 0x800000
	s_movk_i32 s13, 0x4400
	s_add_i32 s33, 0, 0x20000
	s_mov_b32 s22, 0x40000
	s_movk_i32 s23, 0x7fff
	s_mov_b32 s24, 0x80000
	s_mov_b32 s25, 0xc0000
	s_mov_b32 s29, 0x100000
	s_mov_b32 s14, 0x140000
	s_mov_b32 s15, 0x180000
	s_mov_b32 s28, 0x1c0000
	s_mov_b32 s30, 0x3e38aa3b
	s_mov_b32 s52, 0xf149f2ca
	s_mov_b32 s53, 0xc2800000
	s_mov_b64 s[4:5], 0
	s_mov_b64 s[26:27], 0x80
	s_mov_b32 s66, s89
	v_writelane_b32 v254, s74, 63
	v_writelane_b32 v255, s93, 15
	v_readlane_b32 s41, v252, 1
	v_readlane_b32 s42, v252, 2
	v_readlane_b32 s43, v252, 3
	v_readlane_b32 s44, v252, 4
	v_readlane_b32 s45, v252, 5
	v_readlane_b32 s46, v252, 6
	v_readlane_b32 s47, v252, 7
	v_readlane_b32 s48, v252, 8
	v_readlane_b32 s49, v252, 9
	s_branch .LBB0_63

.LBB0_545:
	s_add_i32 s64, s64, 1
	s_mul_i32 s7, s64, s31
	s_mul_hi_u32 s40, s64, s82
	s_add_i32 s40, s40, s7
	s_mul_i32 s7, s64, s82
	s_add_u32 s48, s7, s2
	s_addc_u32 s49, s40, s3
	v_mov_b64_e32 v[2:3], 0x180
	v_cmp_lt_i64_e64 s[40:41], s[48:49], v[2:3]
	v_mov_b64_e32 v[2:3], 0x17f
	v_cmp_gt_i64_e32 vcc, s[48:49], v[2:3]
	s_cbranch_vccnz .LBB0_550
	v_cmp_gt_i64_e32 vcc, s[48:49], v[174:175]
	s_mov_b64 s[84:85], -1
	s_cbranch_vccz .LBB0_548
	s_and_b32 s65, s48, 15
	s_lshl_b32 s88, s65, 8
	s_bfe_u32 s46, s48, 0x30004
	s_mov_b64 s[84:85], 0
	s_mov_b64 s[86:87], s[88:89]

.LBB0_551:
	s_mov_b32 s66, 2
	s_mov_b32 s48, 32

.LBB0_576:
	s_lshl_b32 s7, s16, 5
	s_lshl_b32 s6, s6, 4
	s_add_i32 s6, s6, s7
	s_add_i32 s6, s6, s57
	s_addk_i32 s6, 0xfc00
	s_ashr_i32 s7, s6, 31
	s_lshl_b64 s[6:7], s[6:7], 18
	s_waitcnt lgkmcnt(0)
	v_lshl_add_u64 v[150:151], v[144:145], 0, s[6:7]
	s_and_b64 vcc, exec, s[44:45]
	s_cbranch_vccz .Lmy_pr_outproj_done
	global_store_dwordx4 v[150:151], v[132:135], off
	global_store_dwordx4 v[150:151], v[128:131], off offset:16
	global_store_dwordx4 v[150:151], v[116:119], off offset:512
	global_store_dwordx4 v[150:151], v[102:105], off offset:528
	s_nop 1
	v_add_co_u32_e32 v102, vcc, 0x4000, v150
	s_nop 1
	v_addc_co_u32_e32 v103, vcc, 0, v151, vcc
	global_store_dwordx4 v[102:103], v[124:127], off
	global_store_dwordx4 v[102:103], v[120:123], off offset:16
	global_store_dwordx4 v[102:103], v[94:97], off offset:512
	global_store_dwordx4 v[102:103], v[86:89], off offset:528
	s_nop 1
	v_add_co_u32_e32 v86, vcc, 0x8000, v150
	s_nop 1
	v_addc_co_u32_e32 v87, vcc, 0, v151, vcc
	global_store_dwordx4 v[86:87], v[106:109], off
	global_store_dwordx4 v[86:87], v[98:101], off offset:16
	global_store_dwordx4 v[86:87], v[78:81], off offset:512
	global_store_dwordx4 v[86:87], v[74:77], off offset:528
	s_nop 1
	v_add_co_u32_e32 v74, vcc, 0xc000, v150
	s_nop 1
	v_addc_co_u32_e32 v75, vcc, 0, v151, vcc
	global_store_dwordx4 v[74:75], v[90:93], off
	global_store_dwordx4 v[74:75], v[82:85], off offset:16
	global_store_dwordx4 v[74:75], v[70:73], off offset:512
	global_store_dwordx4 v[74:75], v[66:69], off offset:528
	s_branch .Lmy_pr_outproj_done
	s_nop 1
	v_add_co_u32_e32 v66, vcc, 0x20000, v150
	s_nop 1
	v_addc_co_u32_e32 v67, vcc, 0, v151, vcc
	global_store_dwordx4 v[66:67], v[62:65], off
	global_store_dwordx4 v[66:67], v[58:61], off offset:16
	global_store_dwordx4 v[66:67], v[46:49], off offset:512
	global_store_dwordx4 v[66:67], v[38:41], off offset:528
	s_nop 1
	v_add_co_u32_e32 v38, vcc, 0x24000, v150
	s_nop 1
	v_addc_co_u32_e32 v39, vcc, 0, v151, vcc
	global_store_dwordx4 v[38:39], v[54:57], off
	global_store_dwordx4 v[38:39], v[50:53], off offset:16
	global_store_dwordx4 v[38:39], v[30:33], off offset:512
	global_store_dwordx4 v[38:39], v[22:25], off offset:528
	s_nop 1
	v_add_co_u32_e32 v22, vcc, 0x28000, v150
	s_nop 1
	v_addc_co_u32_e32 v23, vcc, 0, v151, vcc
	global_store_dwordx4 v[22:23], v[42:45], off
	global_store_dwordx4 v[22:23], v[34:37], off offset:16
	global_store_dwordx4 v[22:23], v[14:17], off offset:512
	global_store_dwordx4 v[22:23], v[10:13], off offset:528
	s_nop 1
	v_add_co_u32_e32 v10, vcc, 0x2c000, v150
	s_nop 1
	v_addc_co_u32_e32 v11, vcc, 0, v151, vcc
	global_store_dwordx4 v[10:11], v[26:29], off
	global_store_dwordx4 v[10:11], v[18:21], off offset:16
	global_store_dwordx4 v[10:11], v[6:9], off offset:512
	global_store_dwordx4 v[10:11], v[2:5], off offset:528

.LBB0_638:
	s_ashr_i32 s6, s16, 3
	s_cmpk_gt_i32 s6, 63
	s_cselect_b32 s99, 1, 0
	s_add_i32 s4, s6, 0x2000
	s_ashr_i32 s5, s4, 31
	s_lshl_b64 s[38:39], s[4:5], 12
	v_lshl_add_u64 v[16:17], v[2:3], 0, s[38:39]
	s_waitcnt lgkmcnt(0)
	global_load_dwordx2 v[192:193], v[16:17], off
	s_cmp_eq_u32 s99, 1
	s_cbranch_scc1 .Lmy_fx_outproj_zero
	s_ashr_i32 s7, s6, 31
	s_lshl_b64 s[6:7], s[6:7], 10
	v_lshl_add_u64 v[22:23], v[4:5], 0, s[6:7]
	s_mov_b32 s100, 0x200000
	global_load_dwordx4 v[32:35], v[22:23], off
	v_add_co_u32_e64 v194, s[38:39], s22, v22
	s_nop 1
	v_addc_co_u32_e64 v195, s[38:39], 0, v23, s[38:39]
	global_load_dwordx4 v[36:39], v[194:195], off
	v_add_co_u32_e64 v194, s[38:39], s24, v22
	s_nop 1
	v_addc_co_u32_e64 v195, s[38:39], 0, v23, s[38:39]
	global_load_dwordx4 v[40:43], v[194:195], off
	v_add_co_u32_e64 v194, s[38:39], s25, v22
	s_nop 1
	v_addc_co_u32_e64 v195, s[38:39], 0, v23, s[38:39]
	global_load_dwordx4 v[44:47], v[194:195], off
	v_add_co_u32_e64 v194, s[38:39], s29, v22
	s_nop 1
	v_addc_co_u32_e64 v195, s[38:39], 0, v23, s[38:39]
	global_load_dwordx4 v[48:51], v[194:195], off
	v_add_co_u32_e64 v194, s[38:39], s14, v22
	s_nop 1
	v_addc_co_u32_e64 v195, s[38:39], 0, v23, s[38:39]
	global_load_dwordx4 v[52:55], v[194:195], off
	v_add_co_u32_e64 v194, s[38:39], s15, v22
	s_nop 1
	v_addc_co_u32_e64 v195, s[38:39], 0, v23, s[38:39]
	global_load_dwordx4 v[56:59], v[194:195], off
	v_add_co_u32_e64 v194, s[38:39], s28, v22
	s_nop 1
	v_addc_co_u32_e64 v195, s[38:39], 0, v23, s[38:39]
	global_load_dwordx4 v[60:63], v[194:195], off
	v_add_co_u32_e64 v196, s[38:39], s100, v22
	s_nop 1
	v_addc_co_u32_e64 v197, s[38:39], 0, v23, s[38:39]
	global_load_dwordx4 v[64:67], v[196:197], off
	v_add_co_u32_e64 v194, s[38:39], s22, v196
	s_nop 1
	v_addc_co_u32_e64 v195, s[38:39], 0, v197, s[38:39]
	global_load_dwordx4 v[68:71], v[194:195], off
	v_add_co_u32_e64 v194, s[38:39], s24, v196
	s_nop 1
	v_addc_co_u32_e64 v195, s[38:39], 0, v197, s[38:39]
	global_load_dwordx4 v[72:75], v[194:195], off
	v_add_co_u32_e64 v194, s[38:39], s25, v196
	s_nop 1
	v_addc_co_u32_e64 v195, s[38:39], 0, v197, s[38:39]
	global_load_dwordx4 v[76:79], v[194:195], off
	v_add_co_u32_e64 v194, s[38:39], s29, v196
	s_nop 1
	v_addc_co_u32_e64 v195, s[38:39], 0, v197, s[38:39]
	global_load_dwordx4 v[80:83], v[194:195], off
	v_add_co_u32_e64 v194, s[38:39], s14, v196
	s_nop 1
	v_addc_co_u32_e64 v195, s[38:39], 0, v197, s[38:39]
	global_load_dwordx4 v[84:87], v[194:195], off
	v_add_co_u32_e64 v194, s[38:39], s15, v196
	s_nop 1
	v_addc_co_u32_e64 v195, s[38:39], 0, v197, s[38:39]
	global_load_dwordx4 v[88:91], v[194:195], off
	v_add_co_u32_e64 v194, s[38:39], s28, v196
	s_nop 1
	v_addc_co_u32_e64 v195, s[38:39], 0, v197, s[38:39]
	global_load_dwordx4 v[92:95], v[194:195], off
	s_waitcnt vmcnt(0)
	v_lshlrev_b32_e32 v18, 16, v192
	v_and_b32_e32 v19, 0xffff0000, v192
	v_lshlrev_b32_e32 v20, 16, v193
	v_and_b32_e32 v21, 0xffff0000, v193
	v_pk_add_f32 v[18:19], v[32:33], v[18:19]
	v_pk_add_f32 v[20:21], v[34:35], v[20:21]
	v_pk_add_f32 v[18:19], v[36:37], v[18:19]
	v_pk_add_f32 v[20:21], v[38:39], v[20:21]
	v_pk_add_f32 v[18:19], v[40:41], v[18:19]
	v_pk_add_f32 v[20:21], v[42:43], v[20:21]
	v_pk_add_f32 v[18:19], v[44:45], v[18:19]
	v_pk_add_f32 v[20:21], v[46:47], v[20:21]
	v_pk_add_f32 v[18:19], v[48:49], v[18:19]
	v_pk_add_f32 v[20:21], v[50:51], v[20:21]
	v_pk_add_f32 v[18:19], v[52:53], v[18:19]
	v_pk_add_f32 v[20:21], v[54:55], v[20:21]
	v_pk_add_f32 v[18:19], v[56:57], v[18:19]
	v_pk_add_f32 v[20:21], v[58:59], v[20:21]
	v_pk_add_f32 v[18:19], v[60:61], v[18:19]
	v_pk_add_f32 v[20:21], v[62:63], v[20:21]
	v_pk_add_f32 v[18:19], v[64:65], v[18:19]
	v_pk_add_f32 v[20:21], v[66:67], v[20:21]
	v_pk_add_f32 v[18:19], v[68:69], v[18:19]
	v_pk_add_f32 v[20:21], v[70:71], v[20:21]
	v_pk_add_f32 v[18:19], v[72:73], v[18:19]
	v_pk_add_f32 v[20:21], v[74:75], v[20:21]
	v_pk_add_f32 v[18:19], v[76:77], v[18:19]
	v_pk_add_f32 v[20:21], v[78:79], v[20:21]
	v_pk_add_f32 v[18:19], v[80:81], v[18:19]
	v_pk_add_f32 v[20:21], v[82:83], v[20:21]
	v_pk_add_f32 v[18:19], v[84:85], v[18:19]
	v_pk_add_f32 v[20:21], v[86:87], v[20:21]
	v_pk_add_f32 v[18:19], v[88:89], v[18:19]
	v_pk_add_f32 v[20:21], v[90:91], v[20:21]
	v_pk_add_f32 v[18:19], v[92:93], v[18:19]
	v_pk_add_f32 v[20:21], v[94:95], v[20:21]
	s_branch .Lmy_fx_outproj_join

.Lmy_fx_outproj_join:
	v_mov_b32_e32 v12, v18
	v_mov_b32_e32 v13, v19
	v_mov_b32_e32 v14, v20
	v_mov_b32_e32 v15, v21
	v_mul_f32_e32 v18, v15, v15
	v_mul_f32_e32 v11, v13, v13
	v_fmac_f32_e32 v11, v12, v12
	v_fmac_f32_e32 v18, v14, v14
	v_add_f32_e32 v11, v11, v18
	v_bfe_u32 v18, v12, 16, 1
	v_add3_u32 v12, v12, v18, s23
	v_bfe_u32 v18, v13, 16, 1
	v_lshrrev_b32_e32 v12, 16, v12
	v_add3_u32 v13, v13, v18, s23
	v_and_or_b32 v12, v13, s83, v12
	v_bfe_u32 v13, v14, 16, 1
	v_add3_u32 v13, v14, v13, s23
	v_bfe_u32 v14, v15, 16, 1
	v_lshrrev_b32_e32 v13, 16, v13
	v_add3_u32 v14, v15, v14, s23
	v_and_or_b32 v13, v14, s83, v13
	global_store_dwordx2 v[16:17], v[12:13], off
	ds_bpermute_b32 v12, v1, v11
	s_waitcnt lgkmcnt(0)
	v_add_f32_e32 v11, v11, v12
	ds_bpermute_b32 v12, v6, v11
	s_waitcnt lgkmcnt(0)
	v_add_f32_e32 v11, v11, v12
	ds_bpermute_b32 v12, v7, v11
	s_waitcnt lgkmcnt(0)
	v_add_f32_e32 v11, v11, v12
	ds_bpermute_b32 v12, v8, v11
	s_waitcnt lgkmcnt(0)
	v_add_f32_e32 v11, v11, v12
	ds_bpermute_b32 v12, v9, v11
	s_waitcnt lgkmcnt(0)
	v_add_f32_e32 v11, v11, v12
	ds_bpermute_b32 v12, v10, v11
	s_and_saveexec_b64 s[6:7], vcc
	s_cbranch_execz .LBB0_637
	s_lshl_b64 s[4:5], s[4:5], 7
	s_add_u32 s4, s8, s4
	s_waitcnt lgkmcnt(0)
	v_add_f32_e32 v12, v11, v12
	s_addc_u32 s5, s9, s5
	v_mov_b32_e32 v13, v0
	v_mov_b32_e32 v14, v0
	v_mov_b32_e32 v15, v0
	global_store_dwordx4 v0, v[12:15], s[4:5]
	s_branch .LBB0_637
